# alignment barrier of the leading half moved into the epilogue in the w_in and residual GEMM loops too (residual loads issued before the barrier)
# speedup vs baseline: 1.0177x; 1.0002x over previous
.Lpeel_exit_1:
.LBB0_569:
	v_lshl_add_u32 v150, s46, 8, v197
	s_mov_b64 s[0:1], -1
	s_cmp_gt_u32 s2, 11
	v_ashrrev_i32_e32 v151, 31, v150
	s_cbranch_scc1 .LBB0_571
	s_lshl_b32 s0, s2, 10
	s_add_i32 s0, s0, 0
	v_add_u32_e32 v134, s0, v198
	v_add_u32_e32 v135, 0x20ac0, v134
	v_add_u32_e32 v136, 0x20a80, v134
	v_add_u32_e32 v137, 0x20a40, v134
	v_add_u32_e32 v152, 0x20a00, v134
	v_add_u32_e32 v153, 0x208c0, v134
	v_add_u32_e32 v154, 0x20880, v134
	v_add_u32_e32 v155, 0x20840, v134
	v_add_u32_e32 v156, 0x20800, v134
	ds_read_b32 v134, v135
	ds_read_b32 v164, v136
	ds_read_b32 v162, v137
	ds_read_b32 v158, v152
	ds_read_b32 v160, v153
	ds_read_b32 v166, v154
	ds_read_b32 v168, v155
	ds_read_b32 v170, v156
	s_mov_b64 s[0:1], 0

.LBB0_581:
	v_mov_b32_e32 v137, v136
	s_waitcnt lgkmcnt(0)
	v_mad_i64_i32 v[168:169], s[2:3], v156, s76, v[170:171]
	v_mov_b32_e32 v156, v136
	v_mov_b32_e32 v157, v136
	v_pk_mul_f32 v[174:175], v[156:157], v[116:117]
	v_pk_mul_f32 v[172:173], v[136:137], v[114:115]
	v_pk_mul_f32 v[182:183], v[156:157], v[112:113]
	v_pk_mul_f32 v[184:185], v[136:137], v[110:111]
	v_cvt_pk_bf16_f32 v172, v172, v173
	v_cvt_pk_bf16_f32 v173, v174, v175
	v_cvt_pk_bf16_f32 v174, v184, v185
	v_cvt_pk_bf16_f32 v175, v182, v183
	global_store_dwordx4 v[168:169], v[172:175], off
	v_pk_mul_f32 v[182:183], v[156:157], v[104:105]
	v_pk_mul_f32 v[184:185], v[136:137], v[102:103]
	v_pk_mul_f32 v[174:175], v[156:157], v[108:109]
	v_pk_mul_f32 v[172:173], v[136:137], v[106:107]
	v_pk_mul_f32 v[100:101], v[100:101], v[166:167] op_sel_hi:[1,0]
	v_cvt_pk_bf16_f32 v172, v172, v173
	v_cvt_pk_bf16_f32 v173, v174, v175
	v_cvt_pk_bf16_f32 v174, v184, v185
	v_cvt_pk_bf16_f32 v175, v182, v183
	global_store_dwordx4 v[168:169], v[172:175], off offset:256
	s_cmp_lg_u64 s[18:19], 0
	s_cbranch_scc0 .Lea_l1
	s_barrier
.Lea_l1:
	v_pk_mul_f32 v[98:99], v[98:99], v[166:167] op_sel_hi:[1,0]
	v_pk_mul_f32 v[96:97], v[96:97], v[166:167] op_sel_hi:[1,0]
	v_pk_mul_f32 v[94:95], v[94:95], v[166:167] op_sel_hi:[1,0]
	v_pk_mul_f32 v[92:93], v[92:93], v[166:167] op_sel_hi:[1,0]
	v_pk_mul_f32 v[90:91], v[90:91], v[166:167] op_sel_hi:[1,0]
	v_pk_mul_f32 v[88:89], v[88:89], v[166:167] op_sel_hi:[1,0]
	s_and_b64 vcc, exec, s[0:1]
	v_pk_mul_f32 v[86:87], v[86:87], v[166:167] op_sel_hi:[1,0]
	s_cbranch_vccnz .LBB0_585
	ds_bpermute_b32 v168, v192, v98
	ds_bpermute_b32 v169, v192, v99
	ds_bpermute_b32 v166, v192, v100
	ds_bpermute_b32 v167, v192, v101
	ds_bpermute_b32 v174, v192, v94
	ds_bpermute_b32 v175, v192, v95
	ds_bpermute_b32 v172, v192, v96
	ds_bpermute_b32 v173, v192, v97
	ds_bpermute_b32 v184, v192, v90
	ds_bpermute_b32 v185, v192, v91
	ds_bpermute_b32 v182, v192, v92
	ds_bpermute_b32 v183, v192, v93
	ds_bpermute_b32 v186, v192, v86
	ds_bpermute_b32 v187, v192, v87
	ds_bpermute_b32 v188, v192, v88
	ds_bpermute_b32 v189, v192, v89
	s_and_saveexec_b64 s[30:31], s[6:7]
	s_cbranch_execz .LBB0_584
	s_waitcnt vmcnt(2)
	v_mov_b64_e32 v[202:203], v[218:219]
	v_mov_b64_e32 v[204:205], v[220:221]
	v_mov_b64_e32 v[206:207], v[222:223]
	v_mov_b64_e32 v[208:209], v[224:225]
	v_mov_b64_e32 v[210:211], v[226:227]
	v_mov_b64_e32 v[212:213], v[228:229]
	v_mov_b64_e32 v[214:215], v[230:231]
	v_mov_b64_e32 v[216:217], v[232:233]
	global_load_dwordx4 v[218:221], v[234:235], off offset:3072
	global_load_dwordx4 v[222:225], v[234:235], off offset:3104
	global_load_dwordx4 v[226:229], v[234:235], off offset:3088
	global_load_dwordx4 v[230:233], v[234:235], off offset:3120
	v_xor_b32_e32 v135, 0x80000000, v214
	v_xor_b32_e32 v151, 0x80000000, v215
	v_xor_b32_e32 v155, 0x80000000, v216
	v_xor_b32_e32 v159, 0x80000000, v217
	v_cndmask_b32_e64 v191, v217, v159, s[4:5]
	v_cndmask_b32_e64 v190, v216, v155, s[4:5]
	v_cndmask_b32_e64 v215, v215, v151, s[4:5]
	v_cndmask_b32_e64 v214, v214, v135, s[4:5]
	s_waitcnt lgkmcnt(2)
	v_pk_mul_f32 v[186:187], v[214:215], v[186:187]
	s_waitcnt lgkmcnt(0)
	v_pk_mul_f32 v[188:189], v[190:191], v[188:189]
	v_xor_b32_e32 v135, 0x80000000, v206
	v_xor_b32_e32 v151, 0x80000000, v207
	v_xor_b32_e32 v155, 0x80000000, v208
	v_xor_b32_e32 v159, 0x80000000, v209
	v_pk_fma_f32 v[88:89], v[88:89], v[212:213], v[188:189]
	v_pk_fma_f32 v[86:87], v[86:87], v[210:211], v[186:187]
	v_cndmask_b32_e64 v187, v209, v159, s[4:5]
	v_cndmask_b32_e64 v186, v208, v155, s[4:5]
	v_cndmask_b32_e64 v189, v207, v151, s[4:5]
	v_cndmask_b32_e64 v188, v206, v135, s[4:5]
	v_pk_mul_f32 v[184:185], v[188:189], v[184:185]
	v_pk_mul_f32 v[182:183], v[186:187], v[182:183]
	v_pk_mul_f32 v[174:175], v[214:215], v[174:175]
	v_pk_mul_f32 v[172:173], v[190:191], v[172:173]
	v_pk_mul_f32 v[168:169], v[188:189], v[168:169]
	v_pk_mul_f32 v[166:167], v[186:187], v[166:167]
	v_pk_fma_f32 v[92:93], v[92:93], v[204:205], v[182:183]
	v_pk_fma_f32 v[90:91], v[90:91], v[202:203], v[184:185]
	v_pk_fma_f32 v[96:97], v[96:97], v[212:213], v[172:173]
	v_pk_fma_f32 v[94:95], v[94:95], v[210:211], v[174:175]
	v_pk_fma_f32 v[100:101], v[100:101], v[204:205], v[166:167]
	v_pk_fma_f32 v[98:99], v[98:99], v[202:203], v[168:169]

.Lpeel_exit_2:
.LBB0_640:
	v_lshl_or_b32 v142, s2, 8, v250
	v_lshl_add_u32 v214, s3, 8, v17
	v_ashrrev_i32_e32 v143, 31, v142
	v_lshlrev_b64 v[220:221], 1, v[142:143]
	v_ashrrev_i32_e32 v215, 31, v214
	v_lshl_add_u64 v[182:183], s[84:85], 0, v[220:221]
	v_lshlrev_b64 v[222:223], 11, v[214:215]
	v_lshl_add_u64 v[144:145], v[182:183], 0, v[222:223]
	global_load_dwordx2 v[150:151], v[144:145], off
	global_load_dwordx2 v[152:153], v[144:145], off offset:32
	global_load_dwordx2 v[158:159], v[144:145], off offset:256
	global_load_dwordx2 v[162:163], v[144:145], off offset:288
	v_xor_b32_e32 v135, 16, v241
	v_cmp_lt_i32_e32 vcc, v135, v242
	v_or_b32_e32 v200, 16, v214
	v_ashrrev_i32_e32 v201, 31, v200
	v_cndmask_b32_e32 v135, v241, v135, vcc
	v_or_b32_e32 v156, 32, v214
	v_lshlrev_b32_e32 v253, 2, v135
	v_xor_b32_e32 v135, 32, v241
	v_lshlrev_b64 v[208:209], 11, v[200:201]
	v_ashrrev_i32_e32 v157, 31, v156
	v_or_b32_e32 v146, 48, v214
	v_cmp_lt_i32_e32 vcc, v135, v242
	v_lshl_add_u64 v[144:145], v[182:183], 0, v[208:209]
	v_lshlrev_b64 v[192:193], 11, v[156:157]
	v_ashrrev_i32_e32 v147, 31, v146
	v_cndmask_b32_e32 v135, v241, v135, vcc
	global_load_dwordx2 v[218:219], v[144:145], off
	global_load_dwordx2 v[216:217], v[144:145], off offset:32
	global_load_dwordx2 v[212:213], v[144:145], off offset:256
	global_load_dwordx2 v[210:211], v[144:145], off offset:288
	v_lshl_add_u64 v[144:145], v[182:183], 0, v[192:193]
	v_lshlrev_b64 v[148:149], 11, v[146:147]
	v_lshlrev_b32_e32 v252, 2, v135
	v_mov_b32_e32 v135, v134
	global_load_dwordx2 v[206:207], v[144:145], off
	global_load_dwordx2 v[204:205], v[144:145], off offset:32
	global_load_dwordx2 v[202:203], v[144:145], off offset:256
	global_load_dwordx2 v[198:199], v[144:145], off offset:288
	v_lshl_add_u64 v[144:145], v[182:183], 0, v[148:149]
	global_load_dwordx2 v[170:171], v[144:145], off
	global_load_dwordx2 v[164:165], v[144:145], off offset:32
	global_load_dwordx2 v[160:161], v[144:145], off offset:256
	global_load_dwordx2 v[154:155], v[144:145], off offset:288
	v_add_u32_e32 v144, 0x80, v214
	v_ashrrev_i32_e32 v145, 31, v144
	v_lshl_add_u64 v[222:223], s[84:85], 0, v[222:223]
	v_lshl_add_u64 v[220:221], v[222:223], 0, v[220:221]
	s_lshl_b32 s2, s2, 2
	s_ashr_i32 s3, s2, 31
	s_lshl_b64 s[2:3], s[2:3], 2
	s_add_u32 s22, s42, s2
	s_addc_u32 s23, s43, s3
	s_cmp_lg_u64 s[18:19], 0
	s_cbranch_scc0 .Lea_l2
	s_barrier
.Lea_l2:
	s_waitcnt vmcnt(0)
	v_lshlrev_b32_e32 v166, 16, v150
	v_and_b32_e32 v167, 0xffff0000, v150
	v_lshlrev_b32_e32 v150, 16, v151
	v_and_b32_e32 v151, 0xffff0000, v151
	v_pk_fma_f32 v[236:237], v[134:135], v[132:133], v[150:151]
	v_pk_fma_f32 v[238:239], v[136:137], v[130:131], v[166:167]
	v_lshlrev_b32_e32 v130, 16, v152
	v_and_b32_e32 v131, 0xffff0000, v152
	v_lshlrev_b32_e32 v132, 16, v153
	v_and_b32_e32 v133, 0xffff0000, v153
	v_pk_fma_f32 v[232:233], v[134:135], v[128:129], v[132:133]
	v_pk_fma_f32 v[234:235], v[136:137], v[126:127], v[130:131]
	v_lshlrev_b32_e32 v126, 16, v158
	v_and_b32_e32 v127, 0xffff0000, v158
	v_lshlrev_b32_e32 v128, 16, v159
	v_and_b32_e32 v129, 0xffff0000, v159
	v_pk_fma_f32 v[228:229], v[134:135], v[124:125], v[128:129]
	v_pk_fma_f32 v[230:231], v[136:137], v[122:123], v[126:127]
	v_lshlrev_b32_e32 v124, 16, v163
	v_and_b32_e32 v125, 0xffff0000, v163
	v_add_u32_e32 v126, 0x90, v214
	v_lshlrev_b32_e32 v122, 16, v162
	v_and_b32_e32 v123, 0xffff0000, v162
	v_pk_fma_f32 v[224:225], v[134:135], v[120:121], v[124:125]
	v_lshlrev_b64 v[150:151], 11, v[144:145]
	v_ashrrev_i32_e32 v127, 31, v126
	v_add_u32_e32 v120, 0xa0, v214
	v_pk_fma_f32 v[226:227], v[136:137], v[118:119], v[122:123]
	v_lshl_add_u64 v[118:119], v[182:183], 0, v[150:151]
	v_lshlrev_b64 v[168:169], 11, v[126:127]
	v_ashrrev_i32_e32 v121, 31, v120
	global_load_dwordx2 v[172:173], v[118:119], off
	global_load_dwordx2 v[166:167], v[118:119], off offset:32
	global_load_dwordx2 v[162:163], v[118:119], off offset:256
	global_load_dwordx2 v[158:159], v[118:119], off offset:288
	v_lshl_add_u64 v[118:119], v[182:183], 0, v[168:169]
	v_lshlrev_b64 v[124:125], 11, v[120:121]
	global_load_dwordx2 v[194:195], v[118:119], off
	global_load_dwordx2 v[188:189], v[118:119], off offset:32
	global_load_dwordx2 v[184:185], v[118:119], off offset:256
	global_load_dwordx2 v[174:175], v[118:119], off offset:288
	v_lshl_add_u64 v[118:119], v[182:183], 0, v[124:125]
	global_load_dwordx2 v[152:153], v[118:119], off
	global_load_dwordx2 v[132:133], v[118:119], off offset:32
	global_load_dwordx2 v[130:131], v[118:119], off offset:256
	global_load_dwordx2 v[128:129], v[118:119], off offset:288
	v_add_u32_e32 v118, 0xb0, v214
	v_ashrrev_i32_e32 v119, 31, v118
	v_lshlrev_b64 v[122:123], 11, v[118:119]
	v_lshl_add_u64 v[182:183], v[182:183], 0, v[122:123]
	global_load_dwordx2 v[196:197], v[182:183], off
	global_load_dwordx2 v[190:191], v[182:183], off offset:32
	global_load_dwordx2 v[186:187], v[182:183], off offset:256
	s_nop 0
	global_load_dwordx2 v[182:183], v[182:183], off offset:288
	v_cvt_pk_bf16_f32 v222, v238, v239
	v_cvt_pk_bf16_f32 v223, v236, v237
	global_store_dwordx2 v[220:221], v[222:223], off
	v_mul_f32_e32 v222, v239, v239
	v_mul_f32_e32 v223, v237, v237
	v_fmac_f32_e32 v222, v238, v238
	v_fmac_f32_e32 v223, v236, v236
	v_add_f32_e32 v236, v222, v223
	v_cvt_pk_bf16_f32 v222, v234, v235
	v_cvt_pk_bf16_f32 v223, v232, v233
	global_store_dwordx2 v[220:221], v[222:223], off offset:32
	v_mul_f32_e32 v222, v235, v235
	v_mul_f32_e32 v223, v233, v233
	v_fmac_f32_e32 v222, v234, v234
	v_fmac_f32_e32 v223, v232, v232
	v_add_f32_e32 v222, v222, v223
	v_add_f32_e32 v232, v236, v222
	v_cvt_pk_bf16_f32 v222, v230, v231
	v_cvt_pk_bf16_f32 v223, v228, v229
	global_store_dwordx2 v[220:221], v[222:223], off offset:256
	v_mul_f32_e32 v222, v231, v231
	v_mul_f32_e32 v223, v229, v229
	v_fmac_f32_e32 v222, v230, v230
	v_fmac_f32_e32 v223, v228, v228
	v_add_f32_e32 v222, v222, v223
	v_add_f32_e32 v228, v232, v222
	v_cvt_pk_bf16_f32 v222, v226, v227
	v_cvt_pk_bf16_f32 v223, v224, v225
	global_store_dwordx2 v[220:221], v[222:223], off offset:288
	v_mul_f32_e32 v220, v227, v227
	v_mul_f32_e32 v221, v225, v225
	v_fmac_f32_e32 v220, v226, v226
	v_fmac_f32_e32 v221, v224, v224
	v_add_f32_e32 v220, v220, v221
	v_add_f32_e32 v220, v228, v220
	ds_bpermute_b32 v221, v253, v220
	s_waitcnt lgkmcnt(0)
	v_add_f32_e32 v220, v220, v221
	ds_bpermute_b32 v221, v252, v220
	s_and_saveexec_b64 s[24:25], s[0:1]
	s_cbranch_execz .LBB0_642
	v_lshlrev_b64 v[214:215], 6, v[214:215]
	v_lshl_add_u64 v[214:215], s[22:23], 0, v[214:215]
	s_waitcnt lgkmcnt(0)
	v_add_f32_e32 v220, v220, v221
	global_store_dword v[214:215], v220, off
